# gate/up K-loop restructured: whole K-tile of fragments in registers, 64 MFMAs per segment (2 barriers per K-tile), per-half A/B staging with saddr LDS-DMA; plus E1 trims
# baseline (speedup 1.0000x reference)
.LBB0_1038:
	v_writelane_b32 v254, s30, 43
	v_bfe_i32 v4, v10, 27, 1
	v_lshlrev_b32_e32 v2, 4, v10
	v_writelane_b32 v254, s31, 44
	v_lshrrev_b32_e32 v4, 22, v4
	v_readlane_b32 s0, v254, 24
	v_add_u32_e32 v4, v2, v4
	v_readlane_b32 s1, v254, 25
	s_mov_b32 s2, s0
	s_add_u32 s82, s26, 0x1a400000
	v_and_b32_e32 v4, 0xfffffc00, v4
	s_mul_i32 s1, s2, 0x2c00000
	s_addc_u32 s83, s27, 0
	v_sub_u32_e32 v4, v2, v4
	s_mul_hi_u32 s0, s0, 0x2c00000
	s_add_u32 s90, s39, s1
	v_ashrrev_i32_e32 v3, 31, v10
	v_lshrrev_b32_e32 v5, 4, v4
	s_addc_u32 s91, s46, s0
	s_ashr_i32 s97, s96, 31
	v_lshrrev_b32_e32 v3, 26, v3
	v_bitop3_b32 v4, v5, v4, 32 bitop3:0x6c
	s_lshl_b64 s[0:1], s[96:97], 20
	v_add_u32_e32 v3, v10, v3
	v_ashrrev_i32_e32 v6, 31, v4
	s_add_u32 s6, s82, s0
	v_ashrrev_i32_e32 v3, 6, v3
	v_lshrrev_b32_e32 v6, 26, v6
	s_addc_u32 s7, s83, s1
	s_ashr_i32 s75, s74, 31
	v_lshlrev_b32_e32 v5, 3, v3
	v_add_u32_e32 v6, v4, v6
	s_lshl_b64 s[0:1], s[74:75], 20
	v_and_b32_e32 v5, -16, v5
	v_ashrrev_i32_e32 v7, 6, v6
	v_and_b32_e32 v6, 0xc0, v6
	s_add_u32 s86, s90, s0
	v_add_u32_e32 v5, v7, v5
	v_sub_u32_e32 v4, v4, v6
	s_addc_u32 s87, s91, s1
	v_lshlrev_b32_e32 v3, 5, v3
	v_ashrrev_i16_sdwa v4, v213, sext(v4) dst_sel:DWORD dst_unused:UNUSED_PAD src0_sel:DWORD src1_sel:BYTE_0
	v_lshlrev_b32_e32 v6, 1, v5
	v_lshrrev_b32_e32 v8, 2, v5
	v_and_b32_e32 v7, 3, v7
	s_mov_b32 s1, 0xfffe0
	v_and_b32_e32 v3, 32, v3
	v_bfe_i32 v4, v4, 0, 16
	v_and_b32_e32 v6, 24, v6
	v_and_b32_e32 v8, 4, v8
	v_and_or_b32 v7, v5, s1, v7
	v_or3_b32 v6, v7, v8, v6
	v_add_lshl_u32 v3, v3, v4, 1
	v_add_u32_e32 v2, 0x2000, v2
	v_lshl_add_u32 v130, v5, 12, v3
	v_lshl_add_u32 v202, v6, 12, v3
	v_ashrrev_i32_e32 v3, 31, v2
	v_lshrrev_b32_e32 v3, 22, v3
	v_add_u32_e32 v3, v2, v3
	v_ashrrev_i32_e32 v3, 10, v3
	v_mul_i32_i24_e32 v4, 0x400, v3
	v_sub_u32_e32 v2, v2, v4
	v_lshrrev_b32_e32 v4, 4, v2
	v_bitop3_b32 v2, v4, v2, 32 bitop3:0x6c
	v_ashrrev_i32_e32 v5, 31, v2
	v_lshrrev_b32_e32 v5, 26, v5
	v_lshlrev_b32_e32 v4, 3, v3
	v_add_u32_e32 v5, v2, v5
	v_and_b32_e32 v4, -16, v4
	v_ashrrev_i32_e32 v6, 6, v5
	v_add_u32_e32 v4, v6, v4
	v_and_b32_e32 v6, 3, v6
	v_and_b32_e32 v5, 0xc0, v5
	v_and_or_b32 v6, v4, s1, v6
	s_ashr_i32 s1, s20, 6
	v_sub_u32_e32 v2, v2, v5
	s_lshl_b32 s75, s1, 10
	v_lshlrev_b32_e32 v3, 5, v3
	v_ashrrev_i16_sdwa v2, v213, sext(v2) dst_sel:DWORD dst_unused:UNUSED_PAD src0_sel:DWORD src1_sel:BYTE_0
	v_lshlrev_b32_e32 v5, 1, v4
	v_lshrrev_b32_e32 v7, 2, v4
	s_add_i32 s95, s75, 0
	v_and_b32_e32 v3, 32, v3
	v_bfe_i32 v2, v2, 0, 16
	v_and_b32_e32 v5, 24, v5
	v_and_b32_e32 v7, 4, v7
	s_add_i32 m0, s95, 0x10000
	s_ashr_i32 s0, s20, 8
	v_or3_b32 v5, v6, v7, v5
	v_add_lshl_u32 v2, v3, v2, 1
	s_add_i32 m0, s95, 0x12000
	v_lshl_add_u32 v134, v5, 12, v2
	s_add_u32 s2, s86, 0x80000
	s_addc_u32 s3, s87, 0
	s_add_i32 m0, s95, 0x14000
	s_add_i32 s97, s95, 0x2000
	s_add_i32 m0, s95, 0x16000
	v_writelane_b32 v254, s39, 28
	s_mov_b32 m0, s95
	s_add_u32 s2, s6, 0x80000
	v_writelane_b32 v254, s46, 41
	v_lshl_add_u32 v132, v4, 12, v2
	s_mov_b32 m0, s97
	s_addc_u32 s3, s7, 0
	s_add_i32 s46, s95, 0x4000
	s_mov_b32 m0, s46
	s_add_i32 s48, s95, 0x6000
	s_mov_b32 m0, s48
	v_mov_b32_e32 v135, v203
	v_mov_b32_e32 v131, v203
	v_mov_b32_e32 v133, v203
	s_cmp_eq_u32 s0, 1
	v_lshl_add_u64 v[8:9], s[86:87], 0, v[202:203]
	v_lshl_add_u64 v[6:7], s[86:87], 0, v[134:135]
	v_lshl_add_u64 v[2:3], s[6:7], 0, v[130:131]
	s_cselect_b64 s[16:17], -1, 0
	s_cmp_lg_u32 s0, 1
	v_lshl_add_u64 v[4:5], s[6:7], 0, v[132:133]
	s_cbranch_scc1 .LBB0_1040
.LBB0_1040:
	v_lshrrev_b32_e32 v12, 1, v10
	v_and_b32_e32 v12, 24, v12
	s_add_u32 s18, s26, 0x22200000
	v_and_b32_e32 v11, 15, v10
	v_lshlrev_b32_e32 v13, 1, v12
	v_lshlrev_b32_e32 v10, 2, v10
	s_addc_u32 s19, s27, 0
	v_lshl_or_b32 v141, s0, 6, v11
	v_lshl_or_b32 v11, v11, 6, v13
	s_lshl_b32 s0, s0, 13
	v_and_b32_e32 v10, 32, v10
	v_bitop3_b32 v13, v11, s0, v10 bitop3:0xde
	s_lshl_b32 s0, s1, 5
	s_and_b32 s2, s0, 0x60
	s_add_i32 m0, s95, 0x18000
	v_lshl_add_u64 v[8:9], v[8:9], 0, s[42:43]
	s_lshl_b32 s0, s2, 7
	v_lshl_add_u64 v[6:7], v[6:7], 0, s[42:43]
	s_add_i32 m0, s95, 0x1a000
	s_add_i32 s30, s95, 0x8000
	s_add_i32 s31, s95, 0xa000
	v_bitop3_b32 v142, v11, s0, v10 bitop3:0xde
	v_lshl_add_u64 v[2:3], v[2:3], 0, s[42:43]
	s_mov_b32 m0, s30
	s_add_u32 s0, s86, 0x80080
	v_lshl_add_u64 v[2:3], v[4:5], 0, s[42:43]
	s_mov_b32 m0, s31
	s_addc_u32 s1, s87, 0
	s_add_i32 m0, s95, 0x1c000
	v_lshl_add_u64 v[2:3], s[0:1], 0, v[202:203]
	v_lshl_add_u64 v[2:3], s[0:1], 0, v[134:135]
	s_add_i32 m0, s95, 0x1e000
	s_cmpk_lt_u32 s20, 0x100
	s_cselect_b64 s[20:21], -1, 0
	s_lshr_b32 s54, s68, 3
	v_or_b32_e32 v143, s2, v12
	s_mov_b32 s56, 0
	v_add_u32_e32 v144, 0, v13
	s_and_b32 s98, s16, 1
	s_lshl_b32 s99, s98, 17
	s_lshl_b32 s98, s98, 12
	s_add_i32 s98, s98, s95
	v_add_u32_e32 v130, s99, v130
	v_add_u32_e32 v132, 0x20000, v130
	v_add_u32_e32 v202, s99, v202
	v_add_u32_e32 v131, 0x20000, v202
	s_add_u32 s0, s86, 0x80000
	s_addc_u32 s1, s87, 0
	s_add_i32 m0, s98, 0x10000
	s_nop 0
	global_load_lds_dwordx4 v202, s[86:87]
	s_add_i32 m0, s98, 0x11000
	s_nop 0
	global_load_lds_dwordx4 v131, s[86:87]
	s_add_i32 m0, s98, 0x14000
	s_nop 0
	global_load_lds_dwordx4 v202, s[0:1]
	s_add_i32 m0, s98, 0x15000
	s_nop 0
	global_load_lds_dwordx4 v131, s[0:1]
	s_add_u32 s0, s6, 0x80000
	s_addc_u32 s1, s7, 0
	s_mov_b32 m0, s98
	s_nop 0
	global_load_lds_dwordx4 v130, s[6:7]
	s_add_i32 m0, s98, 0x1000
	s_nop 0
	global_load_lds_dwordx4 v132, s[6:7]
	s_add_i32 m0, s98, 0x4000
	s_nop 0
	global_load_lds_dwordx4 v130, s[0:1]
	s_add_i32 m0, s98, 0x5000
	s_nop 0
	global_load_lds_dwordx4 v132, s[0:1]
	s_waitcnt vmcnt(0)
	s_andn2_b64 vcc, exec, s[16:17]
	s_cbranch_vccnz .Lgu_pro_lead
	s_barrier
.Lgu_pro_lead:
	s_barrier
	s_branch .LBB0_1043

.LBB0_1049:
	s_or_b32 s22, s88, 1
	s_lshl_b64 s[0:1], s[22:23], 7
	s_add_u32 s38, s6, s0
	s_addc_u32 s39, s7, s1
	s_add_i32 s22, s88, 2
	s_lshl_b64 s[0:1], s[22:23], 7
	s_add_u32 s62, s6, s0
	s_addc_u32 s63, s7, s1
	s_and_b64 s[2:3], s[28:29], exec
	s_cselect_b32 s3, s63, s77
	s_cselect_b32 s2, s62, s58
	s_add_u32 s62, s86, s0
	s_addc_u32 s63, s87, s1
	s_and_b64 s[0:1], s[28:29], exec
	s_cselect_b32 s29, s63, s93
	s_cselect_b32 s28, s62, s89
	s_or_b32 s62, s88, 1
	s_mov_b32 s63, 0
	s_lshl_b64 s[62:63], s[62:63], 7
	s_add_u32 s100, s86, s62
	s_addc_u32 s101, s87, s63
	s_add_u32 s0, s100, 0x80000
	s_addc_u32 s1, s101, 0
	s_add_i32 m0, s98, 0x18000
	s_nop 0
	global_load_lds_dwordx4 v202, s[100:101]
	s_add_i32 m0, s98, 0x19000
	s_nop 0
	global_load_lds_dwordx4 v131, s[100:101]
	s_add_i32 m0, s98, 0x1c000
	s_nop 0
	global_load_lds_dwordx4 v202, s[0:1]
	s_add_i32 m0, s98, 0x1d000
	s_nop 0
	global_load_lds_dwordx4 v131, s[0:1]
	v_add_u32_e32 v145, 0x10000, v142
	ds_read_b128 v[136:139], v145
	ds_read_b128 v[146:149], v145 offset:1024
	ds_read_b128 v[150:153], v145 offset:2048
	ds_read_b128 v[154:157], v145 offset:3072
	v_add_u32_e32 v145, 0x14000, v142
	ds_read_b128 v[158:161], v145
	ds_read_b128 v[162:165], v145 offset:1024
	ds_read_b128 v[166:169], v145 offset:2048
	ds_read_b128 v[170:173], v145 offset:3072
	ds_read_b128 v[174:177], v144
	ds_read_b128 v[178:181], v144 offset:1024
	ds_read_b128 v[182:185], v144 offset:2048
	ds_read_b128 v[186:189], v144 offset:3072
	ds_read_b128 v[190:193], v144 offset:4096
	ds_read_b128 v[194:197], v144 offset:5120
	ds_read_b128 v[198:201], v144 offset:6144
	ds_read_b128 v[226:229], v144 offset:7168
	ds_read_b128 v[230:233], v144 offset:16384
	ds_read_b128 v[234:237], v144 offset:17408
	ds_read_b128 v[238:241], v144 offset:18432
	ds_read_b128 v[242:245], v144 offset:19456
	ds_read_b128 v[246:249], v144 offset:20480
	ds_read_b128 v[250:253], v144 offset:21504
	ds_read_b128 v[208:211], v144 offset:22528
	ds_read_b128 v[214:217], v144 offset:23552
	s_add_u32 s0, s38, 0x80000
	s_addc_u32 s1, s39, 0
	s_add_i32 m0, s98, 0x8000
	s_nop 0
	global_load_lds_dwordx4 v130, s[38:39]
	s_add_i32 m0, s98, 0x9000
	s_nop 0
	global_load_lds_dwordx4 v132, s[38:39]
	s_add_i32 m0, s98, 0xc000
	s_nop 0
	global_load_lds_dwordx4 v130, s[0:1]
	s_add_i32 m0, s98, 0xd000
	s_nop 0
	global_load_lds_dwordx4 v132, s[0:1]
	s_and_b64 vcc, exec, s[20:21]
	s_cbranch_vccnz .Lgu_nob_a
	s_waitcnt vmcnt(4)
.Lgu_nob_a:
	s_waitcnt lgkmcnt(0)
	s_barrier
	s_setprio 1
	v_mfma_f32_16x16x32_bf16 v[126:129], v[136:139], v[174:177], v[126:129]
	v_mfma_f32_16x16x32_bf16 v[114:117], v[150:153], v[174:177], v[114:117]
	v_mfma_f32_16x16x32_bf16 v[110:113], v[136:139], v[182:185], v[110:113]
	v_mfma_f32_16x16x32_bf16 v[98:101], v[150:153], v[182:185], v[98:101]
	v_mfma_f32_16x16x32_bf16 v[94:97], v[136:139], v[190:193], v[94:97]
	v_mfma_f32_16x16x32_bf16 v[82:85], v[150:153], v[190:193], v[82:85]
	v_mfma_f32_16x16x32_bf16 v[78:81], v[136:139], v[198:201], v[78:81]
	v_mfma_f32_16x16x32_bf16 v[66:69], v[150:153], v[198:201], v[66:69]
	v_mfma_f32_16x16x32_bf16 v[126:129], v[146:149], v[178:181], v[126:129]
	v_mfma_f32_16x16x32_bf16 v[114:117], v[154:157], v[178:181], v[114:117]
	v_mfma_f32_16x16x32_bf16 v[110:113], v[146:149], v[186:189], v[110:113]
	v_mfma_f32_16x16x32_bf16 v[98:101], v[154:157], v[186:189], v[98:101]
	v_mfma_f32_16x16x32_bf16 v[94:97], v[146:149], v[194:197], v[94:97]
	v_mfma_f32_16x16x32_bf16 v[82:85], v[154:157], v[194:197], v[82:85]
	v_mfma_f32_16x16x32_bf16 v[78:81], v[146:149], v[226:229], v[78:81]
	v_mfma_f32_16x16x32_bf16 v[66:69], v[154:157], v[226:229], v[66:69]
	v_mfma_f32_16x16x32_bf16 v[122:125], v[158:161], v[174:177], v[122:125]
	v_mfma_f32_16x16x32_bf16 v[118:121], v[166:169], v[174:177], v[118:121]
	v_mfma_f32_16x16x32_bf16 v[106:109], v[158:161], v[182:185], v[106:109]
	v_mfma_f32_16x16x32_bf16 v[102:105], v[166:169], v[182:185], v[102:105]
	v_mfma_f32_16x16x32_bf16 v[90:93], v[158:161], v[190:193], v[90:93]
	v_mfma_f32_16x16x32_bf16 v[86:89], v[166:169], v[190:193], v[86:89]
	v_mfma_f32_16x16x32_bf16 v[74:77], v[158:161], v[198:201], v[74:77]
	v_mfma_f32_16x16x32_bf16 v[70:73], v[166:169], v[198:201], v[70:73]
	v_mfma_f32_16x16x32_bf16 v[122:125], v[162:165], v[178:181], v[122:125]
	v_mfma_f32_16x16x32_bf16 v[118:121], v[170:173], v[178:181], v[118:121]
	v_mfma_f32_16x16x32_bf16 v[106:109], v[162:165], v[186:189], v[106:109]
	v_mfma_f32_16x16x32_bf16 v[102:105], v[170:173], v[186:189], v[102:105]
	v_mfma_f32_16x16x32_bf16 v[90:93], v[162:165], v[194:197], v[90:93]
	v_mfma_f32_16x16x32_bf16 v[86:89], v[170:173], v[194:197], v[86:89]
	v_mfma_f32_16x16x32_bf16 v[74:77], v[162:165], v[226:229], v[74:77]
	v_mfma_f32_16x16x32_bf16 v[70:73], v[170:173], v[226:229], v[70:73]
	v_mfma_f32_16x16x32_bf16 v[62:65], v[136:139], v[230:233], v[62:65]
	v_mfma_f32_16x16x32_bf16 v[50:53], v[150:153], v[230:233], v[50:53]
	v_mfma_f32_16x16x32_bf16 v[46:49], v[136:139], v[238:241], v[46:49]
	v_mfma_f32_16x16x32_bf16 v[34:37], v[150:153], v[238:241], v[34:37]
	v_mfma_f32_16x16x32_bf16 v[30:33], v[136:139], v[246:249], v[30:33]
	v_mfma_f32_16x16x32_bf16 v[18:21], v[150:153], v[246:249], v[18:21]
	v_mfma_f32_16x16x32_bf16 v[14:17], v[136:139], v[208:211], v[14:17]
	v_mfma_f32_16x16x32_bf16 v[6:9], v[150:153], v[208:211], v[6:9]
	v_mfma_f32_16x16x32_bf16 v[62:65], v[146:149], v[234:237], v[62:65]
	v_mfma_f32_16x16x32_bf16 v[50:53], v[154:157], v[234:237], v[50:53]
	v_mfma_f32_16x16x32_bf16 v[46:49], v[146:149], v[242:245], v[46:49]
	v_mfma_f32_16x16x32_bf16 v[34:37], v[154:157], v[242:245], v[34:37]
	v_mfma_f32_16x16x32_bf16 v[30:33], v[146:149], v[250:253], v[30:33]
	v_mfma_f32_16x16x32_bf16 v[18:21], v[154:157], v[250:253], v[18:21]
	v_mfma_f32_16x16x32_bf16 v[14:17], v[146:149], v[214:217], v[14:17]
	v_mfma_f32_16x16x32_bf16 v[6:9], v[154:157], v[214:217], v[6:9]
	v_mfma_f32_16x16x32_bf16 v[58:61], v[158:161], v[230:233], v[58:61]
	v_mfma_f32_16x16x32_bf16 v[54:57], v[166:169], v[230:233], v[54:57]
	v_mfma_f32_16x16x32_bf16 v[42:45], v[158:161], v[238:241], v[42:45]
	v_mfma_f32_16x16x32_bf16 v[38:41], v[166:169], v[238:241], v[38:41]
	v_mfma_f32_16x16x32_bf16 v[26:29], v[158:161], v[246:249], v[26:29]
	v_mfma_f32_16x16x32_bf16 v[22:25], v[166:169], v[246:249], v[22:25]
	v_mfma_f32_16x16x32_bf16 v[10:13], v[158:161], v[208:211], v[10:13]
	v_mfma_f32_16x16x32_bf16 v[2:5], v[166:169], v[208:211], v[2:5]
	v_mfma_f32_16x16x32_bf16 v[58:61], v[162:165], v[234:237], v[58:61]
	v_mfma_f32_16x16x32_bf16 v[54:57], v[170:173], v[234:237], v[54:57]
	v_mfma_f32_16x16x32_bf16 v[42:45], v[162:165], v[242:245], v[42:45]
	v_mfma_f32_16x16x32_bf16 v[38:41], v[170:173], v[242:245], v[38:41]
	v_mfma_f32_16x16x32_bf16 v[26:29], v[162:165], v[250:253], v[26:29]
	v_mfma_f32_16x16x32_bf16 v[22:25], v[170:173], v[250:253], v[22:25]
	v_mfma_f32_16x16x32_bf16 v[10:13], v[162:165], v[214:217], v[10:13]
	v_mfma_f32_16x16x32_bf16 v[2:5], v[170:173], v[214:217], v[2:5]
	s_setprio 0
	s_waitcnt vmcnt(0)
	s_barrier
	s_add_u32 s0, s28, 0x80000
	s_addc_u32 s1, s29, 0
	s_add_i32 m0, s98, 0x10000
	s_nop 0
	global_load_lds_dwordx4 v202, s[28:29]
	s_add_i32 m0, s98, 0x11000
	s_nop 0
	global_load_lds_dwordx4 v131, s[28:29]
	s_add_i32 m0, s98, 0x14000
	s_nop 0
	global_load_lds_dwordx4 v202, s[0:1]
	s_add_i32 m0, s98, 0x15000
	s_nop 0
	global_load_lds_dwordx4 v131, s[0:1]
	v_add_u32_e32 v145, 0x18000, v142
	ds_read_b128 v[136:139], v145
	ds_read_b128 v[146:149], v145 offset:1024
	ds_read_b128 v[150:153], v145 offset:2048
	ds_read_b128 v[154:157], v145 offset:3072
	v_add_u32_e32 v145, 0x1c000, v142
	ds_read_b128 v[158:161], v145
	ds_read_b128 v[162:165], v145 offset:1024
	ds_read_b128 v[166:169], v145 offset:2048
	ds_read_b128 v[170:173], v145 offset:3072
	ds_read_b128 v[174:177], v144 offset:32768
	ds_read_b128 v[178:181], v144 offset:33792
	ds_read_b128 v[182:185], v144 offset:34816
	ds_read_b128 v[186:189], v144 offset:35840
	ds_read_b128 v[190:193], v144 offset:36864
	ds_read_b128 v[194:197], v144 offset:37888
	ds_read_b128 v[198:201], v144 offset:38912
	ds_read_b128 v[226:229], v144 offset:39936
	ds_read_b128 v[230:233], v144 offset:49152
	ds_read_b128 v[234:237], v144 offset:50176
	ds_read_b128 v[238:241], v144 offset:51200
	ds_read_b128 v[242:245], v144 offset:52224
	ds_read_b128 v[246:249], v144 offset:53248
	ds_read_b128 v[250:253], v144 offset:54272
	ds_read_b128 v[208:211], v144 offset:55296
	ds_read_b128 v[214:217], v144 offset:56320
	s_add_u32 s0, s2, 0x80000
	s_addc_u32 s1, s3, 0
	s_mov_b32 m0, s98
	s_nop 0
	global_load_lds_dwordx4 v130, s[2:3]
	s_add_i32 m0, s98, 0x1000
	s_nop 0
	global_load_lds_dwordx4 v132, s[2:3]
	s_add_i32 m0, s98, 0x4000
	s_nop 0
	global_load_lds_dwordx4 v130, s[0:1]
	s_add_i32 m0, s98, 0x5000
	s_nop 0
	global_load_lds_dwordx4 v132, s[0:1]
	s_and_b64 vcc, exec, s[20:21]
	s_cbranch_vccnz .Lgu_nob_b
	s_waitcnt vmcnt(4)
.Lgu_nob_b:
	s_waitcnt lgkmcnt(0)
	s_barrier
	s_setprio 1
	v_mfma_f32_16x16x32_bf16 v[126:129], v[136:139], v[174:177], v[126:129]
	v_mfma_f32_16x16x32_bf16 v[114:117], v[150:153], v[174:177], v[114:117]
	v_mfma_f32_16x16x32_bf16 v[110:113], v[136:139], v[182:185], v[110:113]
	v_mfma_f32_16x16x32_bf16 v[98:101], v[150:153], v[182:185], v[98:101]
	v_mfma_f32_16x16x32_bf16 v[94:97], v[136:139], v[190:193], v[94:97]
	v_mfma_f32_16x16x32_bf16 v[82:85], v[150:153], v[190:193], v[82:85]
	v_mfma_f32_16x16x32_bf16 v[78:81], v[136:139], v[198:201], v[78:81]
	v_mfma_f32_16x16x32_bf16 v[66:69], v[150:153], v[198:201], v[66:69]
	v_mfma_f32_16x16x32_bf16 v[126:129], v[146:149], v[178:181], v[126:129]
	v_mfma_f32_16x16x32_bf16 v[114:117], v[154:157], v[178:181], v[114:117]
	v_mfma_f32_16x16x32_bf16 v[110:113], v[146:149], v[186:189], v[110:113]
	v_mfma_f32_16x16x32_bf16 v[98:101], v[154:157], v[186:189], v[98:101]
	v_mfma_f32_16x16x32_bf16 v[94:97], v[146:149], v[194:197], v[94:97]
	v_mfma_f32_16x16x32_bf16 v[82:85], v[154:157], v[194:197], v[82:85]
	v_mfma_f32_16x16x32_bf16 v[78:81], v[146:149], v[226:229], v[78:81]
	v_mfma_f32_16x16x32_bf16 v[66:69], v[154:157], v[226:229], v[66:69]
	v_mfma_f32_16x16x32_bf16 v[122:125], v[158:161], v[174:177], v[122:125]
	v_mfma_f32_16x16x32_bf16 v[118:121], v[166:169], v[174:177], v[118:121]
	v_mfma_f32_16x16x32_bf16 v[106:109], v[158:161], v[182:185], v[106:109]
	v_mfma_f32_16x16x32_bf16 v[102:105], v[166:169], v[182:185], v[102:105]
	v_mfma_f32_16x16x32_bf16 v[90:93], v[158:161], v[190:193], v[90:93]
	v_mfma_f32_16x16x32_bf16 v[86:89], v[166:169], v[190:193], v[86:89]
	v_mfma_f32_16x16x32_bf16 v[74:77], v[158:161], v[198:201], v[74:77]
	v_mfma_f32_16x16x32_bf16 v[70:73], v[166:169], v[198:201], v[70:73]
	v_mfma_f32_16x16x32_bf16 v[122:125], v[162:165], v[178:181], v[122:125]
	v_mfma_f32_16x16x32_bf16 v[118:121], v[170:173], v[178:181], v[118:121]
	v_mfma_f32_16x16x32_bf16 v[106:109], v[162:165], v[186:189], v[106:109]
	v_mfma_f32_16x16x32_bf16 v[102:105], v[170:173], v[186:189], v[102:105]
	v_mfma_f32_16x16x32_bf16 v[90:93], v[162:165], v[194:197], v[90:93]
	v_mfma_f32_16x16x32_bf16 v[86:89], v[170:173], v[194:197], v[86:89]
	v_mfma_f32_16x16x32_bf16 v[74:77], v[162:165], v[226:229], v[74:77]
	v_mfma_f32_16x16x32_bf16 v[70:73], v[170:173], v[226:229], v[70:73]
	v_mfma_f32_16x16x32_bf16 v[62:65], v[136:139], v[230:233], v[62:65]
	v_mfma_f32_16x16x32_bf16 v[50:53], v[150:153], v[230:233], v[50:53]
	v_mfma_f32_16x16x32_bf16 v[46:49], v[136:139], v[238:241], v[46:49]
	v_mfma_f32_16x16x32_bf16 v[34:37], v[150:153], v[238:241], v[34:37]
	v_mfma_f32_16x16x32_bf16 v[30:33], v[136:139], v[246:249], v[30:33]
	v_mfma_f32_16x16x32_bf16 v[18:21], v[150:153], v[246:249], v[18:21]
	v_mfma_f32_16x16x32_bf16 v[14:17], v[136:139], v[208:211], v[14:17]
	v_mfma_f32_16x16x32_bf16 v[6:9], v[150:153], v[208:211], v[6:9]
	v_mfma_f32_16x16x32_bf16 v[62:65], v[146:149], v[234:237], v[62:65]
	v_mfma_f32_16x16x32_bf16 v[50:53], v[154:157], v[234:237], v[50:53]
	v_mfma_f32_16x16x32_bf16 v[46:49], v[146:149], v[242:245], v[46:49]
	v_mfma_f32_16x16x32_bf16 v[34:37], v[154:157], v[242:245], v[34:37]
	v_mfma_f32_16x16x32_bf16 v[30:33], v[146:149], v[250:253], v[30:33]
	v_mfma_f32_16x16x32_bf16 v[18:21], v[154:157], v[250:253], v[18:21]
	v_mfma_f32_16x16x32_bf16 v[14:17], v[146:149], v[214:217], v[14:17]
	v_mfma_f32_16x16x32_bf16 v[6:9], v[154:157], v[214:217], v[6:9]
	v_mfma_f32_16x16x32_bf16 v[58:61], v[158:161], v[230:233], v[58:61]
	v_mfma_f32_16x16x32_bf16 v[54:57], v[166:169], v[230:233], v[54:57]
	v_mfma_f32_16x16x32_bf16 v[42:45], v[158:161], v[238:241], v[42:45]
	v_mfma_f32_16x16x32_bf16 v[38:41], v[166:169], v[238:241], v[38:41]
	v_mfma_f32_16x16x32_bf16 v[26:29], v[158:161], v[246:249], v[26:29]
	v_mfma_f32_16x16x32_bf16 v[22:25], v[166:169], v[246:249], v[22:25]
	v_mfma_f32_16x16x32_bf16 v[10:13], v[158:161], v[208:211], v[10:13]
	v_mfma_f32_16x16x32_bf16 v[2:5], v[166:169], v[208:211], v[2:5]
	v_mfma_f32_16x16x32_bf16 v[58:61], v[162:165], v[234:237], v[58:61]
	v_mfma_f32_16x16x32_bf16 v[54:57], v[170:173], v[234:237], v[54:57]
	v_mfma_f32_16x16x32_bf16 v[42:45], v[162:165], v[242:245], v[42:45]
	v_mfma_f32_16x16x32_bf16 v[38:41], v[170:173], v[242:245], v[38:41]
	v_mfma_f32_16x16x32_bf16 v[26:29], v[162:165], v[250:253], v[26:29]
	v_mfma_f32_16x16x32_bf16 v[22:25], v[170:173], v[250:253], v[22:25]
	v_mfma_f32_16x16x32_bf16 v[10:13], v[162:165], v[214:217], v[10:13]
	v_mfma_f32_16x16x32_bf16 v[2:5], v[170:173], v[214:217], v[2:5]
	s_setprio 0
	s_waitcnt vmcnt(0)
	s_barrier
	s_cmp_gt_u32 s88, 29
	s_mov_b32 s88, s22
	s_cbranch_scc1 .LBB0_1061

.LBB0_1066:
	v_mov_b32_e32 v208, 0x260
	v_mov_b32_e32 v209, 0xc000
	v_mov_b32_e32 v210, 0x1000
	v_mov_b32_e32 v211, 0x2000
	v_mbcnt_lo_u32_b32 v214, -1, 0
	v_mbcnt_hi_u32_b32 v214, -1, v214
	v_and_b32_e32 v215, 64, v214
	v_add_u32_e32 v215, 64, v215
	v_xor_b32_e32 v216, 1, v214
	v_xor_b32_e32 v217, 2, v214
	s_waitcnt vmcnt(0)
	v_readlane_b32 s30, v254, 43
	v_readlane_b32 s97, v254, 19
	s_movk_i32 s38, 0x2ff
	s_mov_b32 s92, 0x30000
	v_readlane_b32 s39, v254, 28
	v_readlane_b32 s46, v254, 41
	v_readlane_b32 s31, v254, 44
	s_barrier

	.amdhsa_kernel _Z10fwd_kernel6Params
		.amdhsa_group_segment_fixed_size 0
		.amdhsa_private_segment_fixed_size 0
		.amdhsa_kernarg_size 424
		.amdhsa_user_sgpr_count 2
		.amdhsa_user_sgpr_dispatch_ptr 0
		.amdhsa_user_sgpr_queue_ptr 0
		.amdhsa_user_sgpr_kernarg_segment_ptr 1
		.amdhsa_user_sgpr_dispatch_id 0
		.amdhsa_user_sgpr_kernarg_preload_length 0
		.amdhsa_user_sgpr_kernarg_preload_offset 0
		.amdhsa_user_sgpr_private_segment_size 0
		.amdhsa_uses_dynamic_stack 0
		.amdhsa_enable_private_segment 0
		.amdhsa_system_sgpr_workgroup_id_x 1
		.amdhsa_system_sgpr_workgroup_id_y 0
		.amdhsa_system_sgpr_workgroup_id_z 0
		.amdhsa_system_sgpr_workgroup_info 0
		.amdhsa_system_vgpr_workitem_id 0
		.amdhsa_next_free_vgpr 255
		.amdhsa_next_free_sgpr 102
		.amdhsa_accum_offset 256
		.amdhsa_reserve_vcc 1
		.amdhsa_float_round_mode_32 0
		.amdhsa_float_round_mode_16_64 0
		.amdhsa_float_denorm_mode_32 3
		.amdhsa_float_denorm_mode_16_64 3
		.amdhsa_dx10_clamp 1
		.amdhsa_ieee_mode 1
		.amdhsa_fp16_overflow 0
		.amdhsa_tg_split 0
		.amdhsa_exception_fp_ieee_invalid_op 0
		.amdhsa_exception_fp_denorm_src 0
		.amdhsa_exception_fp_ieee_div_zero 0
		.amdhsa_exception_fp_ieee_overflow 0
		.amdhsa_exception_fp_ieee_underflow 0
		.amdhsa_exception_fp_ieee_inexact 0
		.amdhsa_exception_int_div_zero 0
	.end_amdhsa_kernel

amdhsa.kernels:
  - .agpr_count:     0
    .args:
      - .offset:         0
        .size:           168
        .value_kind:     by_value
      - .offset:         168
        .size:           4
        .value_kind:     hidden_block_count_x
      - .offset:         172
        .size:           4
        .value_kind:     hidden_block_count_y
      - .offset:         176
        .size:           4
        .value_kind:     hidden_block_count_z
      - .offset:         180
        .size:           2
        .value_kind:     hidden_group_size_x
      - .offset:         182
        .size:           2
        .value_kind:     hidden_group_size_y
      - .offset:         184
        .size:           2
        .value_kind:     hidden_group_size_z
      - .offset:         186
        .size:           2
        .value_kind:     hidden_remainder_x
      - .offset:         188
        .size:           2
        .value_kind:     hidden_remainder_y
      - .offset:         190
        .size:           2
        .value_kind:     hidden_remainder_z
      - .offset:         208
        .size:           8
        .value_kind:     hidden_global_offset_x
      - .offset:         216
        .size:           8
        .value_kind:     hidden_global_offset_y
      - .offset:         224
        .size:           8
        .value_kind:     hidden_global_offset_z
      - .offset:         232
        .size:           2
        .value_kind:     hidden_grid_dims
      - .offset:         288
        .size:           4
        .value_kind:     hidden_dynamic_lds_size
    .group_segment_fixed_size: 0
    .kernarg_segment_align: 8
    .kernarg_segment_size: 424
    .language:       OpenCL C
    .language_version:
      - 2
      - 0
    .max_flat_workgroup_size: 512
    .name:           _Z10fwd_kernel6Params
    .private_segment_fixed_size: 0
    .sgpr_count:     108
    .sgpr_spill_count: 70
    .symbol:         _Z10fwd_kernel6Params.kd
    .uniform_work_group_size: 1
    .uses_dynamic_stack: false
    .vgpr_count:     255
    .vgpr_spill_count: 0
    .wavefront_size: 64
